# adaLN GEMV (phase 0): the 32 strided weight rows of a loop trip are touched together at the top of the trip so the four serial load batches hit in cache
# baseline (speedup 1.0000x reference)
; template <int LO, int HI>
; DEV void run_phases(LAS unsigned char* lds, const int ph_lo, const int ph_hi, const int G, const int wave0, unsigned& nbar) {
;     ...
;                     for (int k = wave * 128; k < wave * 128 + 128; ++k) { const float wv = wm[(size_t)k * 6144];
; #pragma unroll
;                         for (int r = 0; r < 9; ++r) acc9[r] += sl[r * 1024 + k] * wv; }
.LBB0_14:
	s_add_i32 s90, s18, 0
	v_mad_i64_i32 v[112:113], s[92:93], s90, v61, v[70:71]
	global_load_dword v114, v[112:113], off
	s_add_i32 s90, s18, 1
	v_mad_i64_i32 v[112:113], s[92:93], s90, v61, v[70:71]
	global_load_dword v114, v[112:113], off
	s_add_i32 s90, s18, 2
	v_mad_i64_i32 v[112:113], s[92:93], s90, v61, v[70:71]
	global_load_dword v114, v[112:113], off
	s_add_i32 s90, s18, 3
	v_mad_i64_i32 v[112:113], s[92:93], s90, v61, v[70:71]
	global_load_dword v114, v[112:113], off
	s_add_i32 s90, s18, 4
	v_mad_i64_i32 v[112:113], s[92:93], s90, v61, v[70:71]
	global_load_dword v114, v[112:113], off
	s_add_i32 s90, s18, 5
	v_mad_i64_i32 v[112:113], s[92:93], s90, v61, v[70:71]
	global_load_dword v114, v[112:113], off
	s_add_i32 s90, s18, 6
	v_mad_i64_i32 v[112:113], s[92:93], s90, v61, v[70:71]
	global_load_dword v114, v[112:113], off
	s_add_i32 s90, s18, 7
	v_mad_i64_i32 v[112:113], s[92:93], s90, v61, v[70:71]
	global_load_dword v114, v[112:113], off
	s_add_i32 s90, s18, 8
	v_mad_i64_i32 v[112:113], s[92:93], s90, v61, v[70:71]
	global_load_dword v114, v[112:113], off
	s_add_i32 s90, s18, 9
	v_mad_i64_i32 v[112:113], s[92:93], s90, v61, v[70:71]
	global_load_dword v114, v[112:113], off
	s_add_i32 s90, s18, 10
	v_mad_i64_i32 v[112:113], s[92:93], s90, v61, v[70:71]
	global_load_dword v114, v[112:113], off
	s_add_i32 s90, s18, 11
	v_mad_i64_i32 v[112:113], s[92:93], s90, v61, v[70:71]
	global_load_dword v114, v[112:113], off
	s_add_i32 s90, s18, 12
	v_mad_i64_i32 v[112:113], s[92:93], s90, v61, v[70:71]
	global_load_dword v114, v[112:113], off
	s_add_i32 s90, s18, 13
	v_mad_i64_i32 v[112:113], s[92:93], s90, v61, v[70:71]
	global_load_dword v114, v[112:113], off
	s_add_i32 s90, s18, 14
	v_mad_i64_i32 v[112:113], s[92:93], s90, v61, v[70:71]
	global_load_dword v114, v[112:113], off
	s_add_i32 s90, s18, 15
	v_mad_i64_i32 v[112:113], s[92:93], s90, v61, v[70:71]
	global_load_dword v114, v[112:113], off
	s_add_i32 s90, s18, 16
	v_mad_i64_i32 v[112:113], s[92:93], s90, v61, v[70:71]
	global_load_dword v114, v[112:113], off
	s_add_i32 s90, s18, 17
	v_mad_i64_i32 v[112:113], s[92:93], s90, v61, v[70:71]
	global_load_dword v114, v[112:113], off
	s_add_i32 s90, s18, 18
	v_mad_i64_i32 v[112:113], s[92:93], s90, v61, v[70:71]
	global_load_dword v114, v[112:113], off
	s_add_i32 s90, s18, 19
	v_mad_i64_i32 v[112:113], s[92:93], s90, v61, v[70:71]
	global_load_dword v114, v[112:113], off
	s_add_i32 s90, s18, 20
	v_mad_i64_i32 v[112:113], s[92:93], s90, v61, v[70:71]
	global_load_dword v114, v[112:113], off
	s_add_i32 s90, s18, 21
	v_mad_i64_i32 v[112:113], s[92:93], s90, v61, v[70:71]
	global_load_dword v114, v[112:113], off
	s_add_i32 s90, s18, 22
	v_mad_i64_i32 v[112:113], s[92:93], s90, v61, v[70:71]
	global_load_dword v114, v[112:113], off
	s_add_i32 s90, s18, 23
	v_mad_i64_i32 v[112:113], s[92:93], s90, v61, v[70:71]
	global_load_dword v114, v[112:113], off
	s_add_i32 s90, s18, 24
	v_mad_i64_i32 v[112:113], s[92:93], s90, v61, v[70:71]
	global_load_dword v114, v[112:113], off
	s_add_i32 s90, s18, 25
	v_mad_i64_i32 v[112:113], s[92:93], s90, v61, v[70:71]
	global_load_dword v114, v[112:113], off
	s_add_i32 s90, s18, 26
	v_mad_i64_i32 v[112:113], s[92:93], s90, v61, v[70:71]
	global_load_dword v114, v[112:113], off
	s_add_i32 s90, s18, 27
	v_mad_i64_i32 v[112:113], s[92:93], s90, v61, v[70:71]
	global_load_dword v114, v[112:113], off
	s_add_i32 s90, s18, 28
	v_mad_i64_i32 v[112:113], s[92:93], s90, v61, v[70:71]
	global_load_dword v114, v[112:113], off
	s_add_i32 s90, s18, 29
	v_mad_i64_i32 v[112:113], s[92:93], s90, v61, v[70:71]
	global_load_dword v114, v[112:113], off
	s_add_i32 s90, s18, 30
	v_mad_i64_i32 v[112:113], s[92:93], s90, v61, v[70:71]
	global_load_dword v114, v[112:113], off
	s_add_i32 s90, s18, 31
	v_mad_i64_i32 v[112:113], s[92:93], s90, v61, v[70:71]
	global_load_dword v114, v[112:113], off
	s_lshl_b32 s19, s18, 2
	s_add_i32 s19, s19, 0
	v_mov_b32_e32 v62, s19
	ds_read_b128 v[10:13], v62 offset:16384
	ds_read_b128 v[26:29], v62 offset:20480
	ds_read_b128 v[14:17], v62 offset:24576
	ds_read_b128 v[34:37], v62 offset:4096
	ds_read_b128 v[2:5], v62 offset:4112
	ds_read_b128 v[30:33], v62 offset:8192
	ds_read_b128 v[22:25], v62 offset:8208
	ds_read_b128 v[42:45], v62 offset:12288
	ds_read_b128 v[6:9], v62 offset:12304
	ds_read_b128 v[18:21], v62 offset:16400
	s_waitcnt lgkmcnt(4)
	v_mov_b32_e32 v84, v30
	v_mov_b32_e32 v85, v34
	v_mov_b32_e32 v86, v10
	s_waitcnt lgkmcnt(2)
	v_mov_b32_e32 v87, v42
	v_mov_b32_e32 v34, v31
	v_mov_b32_e32 v42, v11
	v_mov_b32_e32 v50, v32
	v_mov_b32_e32 v51, v36
	v_mov_b32_e32 v36, v33
	v_mov_b32_e32 v52, v12
	v_mov_b32_e32 v53, v44
	v_mov_b32_e32 v44, v13
	ds_read_b128 v[30:33], v62 offset:24592
	ds_read_b128 v[10:13], v62 offset:20496
	v_mov_b32_e32 v88, v14
	v_mov_b32_e32 v89, v26
	v_mov_b32_e32 v26, v15
	v_mov_b32_e32 v54, v16
	v_mov_b32_e32 v55, v28
	v_mov_b32_e32 v28, v17
	ds_read_b128 v[80:83], v62 offset:32768
	ds_read_b128 v[38:41], v62 offset:32784
	ds_read_b128 v[46:49], v62 offset:28672
	ds_read_b128 v[14:17], v62 offset:28688
	s_or_b32 s19, s18, 1
	s_or_b32 s31, s18, 3
	s_waitcnt lgkmcnt(3)
	v_mov_b32_e32 v90, v80
	s_waitcnt lgkmcnt(1)
	v_mov_b32_e32 v91, v46
	v_mov_b32_e32 v46, v81
	v_mad_i64_i32 v[80:81], s[34:35], s18, v61, v[70:71]
	global_load_dword v80, v[80:81], off
	v_mov_b32_e32 v56, v82
	v_mov_b32_e32 v57, v48
	v_mov_b32_e32 v48, v83
	s_or_b32 s36, s18, 5
	s_or_b32 s38, s18, 7
	s_or_b32 s21, s18, 2
	v_mad_i64_i32 v[96:97], s[34:35], s36, v61, v[70:71]
	v_mad_i64_i32 v[100:101], s[34:35], s38, v61, v[70:71]
	s_or_b32 s33, s18, 4
	v_mad_i64_i32 v[94:95], s[34:35], s33, v61, v[70:71]
	s_or_b32 s37, s18, 6
	v_mad_i64_i32 v[98:99], s[34:35], s37, v61, v[70:71]
	s_or_b32 s39, s18, 8
	v_mad_i64_i32 v[102:103], s[34:35], s39, v61, v[70:71]
	s_or_b32 s36, s18, 13
	s_or_b32 s38, s18, 15
	s_or_b32 s33, s18, 12
	s_or_b32 s37, s18, 14
	s_or_b32 s39, s18, 16
	s_waitcnt vmcnt(0)
; template <int LO, int HI>
; DEV void run_phases(LAS unsigned char* lds, const int ph_lo, const int ph_hi, const int G, const int wave0, unsigned& nbar) {
;     ...
;                     for (int k = wave * 128; k < wave * 128 + 128; ++k) { const float wv = wm[(size_t)k * 6144];
; #pragma unroll
;                         for (int r = 0; r < 9; ++r) acc9[r] += sl[r * 1024 + k] * wv; }
	v_pk_fma_f32 v[82:83], v[80:81], v[84:85], v[78:79] op_sel_hi:[0,1,1]
	v_pk_fma_f32 v[84:85], v[80:81], v[86:87], v[76:77] op_sel_hi:[0,1,1]
	v_pk_fma_f32 v[86:87], v[80:81], v[88:89], v[74:75] op_sel_hi:[0,1,1]
	v_pk_fma_f32 v[88:89], v[80:81], v[90:91], v[72:73] op_sel_hi:[0,1,1]
	ds_read_b128 v[72:75], v62
	ds_read_b128 v[76:79], v62 offset:16
	v_mad_i64_i32 v[90:91], s[34:35], s31, v61, v[70:71]
	global_load_dword v90, v[90:91], off
	s_waitcnt lgkmcnt(1)
	v_fmac_f32_e32 v93, v80, v72
	v_mad_i64_i32 v[80:81], s[34:35], s19, v61, v[70:71]
	global_load_dword v72, v[80:81], off
	s_or_b32 s19, s18, 9
	global_load_dword v96, v[96:97], off
	s_or_b32 s31, s18, 11
	global_load_dword v100, v[100:101], off
	v_mad_i64_i32 v[80:81], s[34:35], s21, v61, v[70:71]
	global_load_dword v80, v[80:81], off
	s_or_b32 s21, s18, 10
	global_load_dword v94, v[94:95], off
	s_waitcnt vmcnt(4)
	v_pk_fma_f32 v[34:35], v[72:73], v[34:35], v[82:83] op_sel_hi:[0,1,1]
	global_load_dword v98, v[98:99], off
	v_pk_fma_f32 v[42:43], v[72:73], v[42:43], v[84:85] op_sel_hi:[0,1,1]
	global_load_dword v102, v[102:103], off
	v_pk_fma_f32 v[26:27], v[72:73], v[26:27], v[86:87] op_sel_hi:[0,1,1]
	v_pk_fma_f32 v[46:47], v[72:73], v[46:47], v[88:89] op_sel_hi:[0,1,1]
	v_fmac_f32_e32 v93, v72, v73
	s_waitcnt vmcnt(3)
	v_pk_fma_f32 v[34:35], v[80:81], v[50:51], v[34:35] op_sel_hi:[0,1,1]
	v_pk_fma_f32 v[42:43], v[80:81], v[52:53], v[42:43] op_sel_hi:[0,1,1]
	v_pk_fma_f32 v[26:27], v[80:81], v[54:55], v[26:27] op_sel_hi:[0,1,1]
	v_pk_fma_f32 v[46:47], v[80:81], v[56:57], v[46:47] op_sel_hi:[0,1,1]
	v_pk_fma_f32 v[34:35], v[90:91], v[36:37], v[34:35] op_sel_hi:[0,1,1]
	v_pk_fma_f32 v[36:37], v[90:91], v[44:45], v[42:43] op_sel_hi:[0,1,1]
	v_pk_fma_f32 v[26:27], v[90:91], v[28:29], v[26:27] op_sel_hi:[0,1,1]
	v_pk_fma_f32 v[28:29], v[90:91], v[48:49], v[46:47] op_sel_hi:[0,1,1]
	v_mov_b32_e32 v42, v22
	v_mov_b32_e32 v43, v2
	v_mov_b32_e32 v2, v23
	v_mov_b32_e32 v44, v24
	v_mov_b32_e32 v45, v4
	v_mov_b32_e32 v4, v25
	v_mov_b32_e32 v22, v18
	v_mov_b32_e32 v23, v6
	v_mov_b32_e32 v24, v30
	v_mov_b32_e32 v25, v10
	v_mov_b32_e32 v10, v31
	v_mov_b32_e32 v30, v32
	v_mov_b32_e32 v31, v12
	v_mov_b32_e32 v12, v33
	v_mov_b32_e32 v32, v38
	v_mov_b32_e32 v33, v14
	v_mov_b32_e32 v6, v19
	v_mov_b32_e32 v14, v39
	s_waitcnt vmcnt(2)
	v_pk_fma_f32 v[34:35], v[94:95], v[42:43], v[34:35] op_sel_hi:[0,1,1]
	v_pk_fma_f32 v[22:23], v[94:95], v[22:23], v[36:37] op_sel_hi:[0,1,1]
	v_pk_fma_f32 v[24:25], v[94:95], v[24:25], v[26:27] op_sel_hi:[0,1,1]
	v_pk_fma_f32 v[26:27], v[94:95], v[32:33], v[28:29] op_sel_hi:[0,1,1]
	v_mov_b32_e32 v46, v20
	v_mov_b32_e32 v47, v8
	v_mov_b32_e32 v48, v40
	v_mov_b32_e32 v49, v16
	v_pk_fma_f32 v[2:3], v[96:97], v[2:3], v[34:35] op_sel_hi:[0,1,1]
	v_pk_fma_f32 v[6:7], v[96:97], v[6:7], v[22:23] op_sel_hi:[0,1,1]
	v_pk_fma_f32 v[10:11], v[96:97], v[10:11], v[24:25] op_sel_hi:[0,1,1]
	v_pk_fma_f32 v[14:15], v[96:97], v[14:15], v[26:27] op_sel_hi:[0,1,1]
	v_mov_b32_e32 v8, v21
	v_mov_b32_e32 v16, v41
	ds_read_b128 v[18:21], v62 offset:4128
	ds_read_b128 v[38:41], v62 offset:8224
	ds_read_b128 v[34:37], v62 offset:8240
	ds_read_b128 v[22:25], v62 offset:12320
	v_fmac_f32_e32 v93, v80, v74
	v_fmac_f32_e32 v93, v90, v75
	s_waitcnt lgkmcnt(4)
	v_fmac_f32_e32 v93, v94, v76
	v_fmac_f32_e32 v93, v96, v77
	ds_read_b128 v[26:29], v62 offset:16432
	s_waitcnt lgkmcnt(3)
	v_mov_b32_e32 v80, v38
	v_mov_b32_e32 v72, v40
	v_mad_i64_i32 v[96:97], s[34:35], s36, v61, v[70:71]
	v_mad_i64_i32 v[94:95], s[34:35], s33, v61, v[70:71]
	s_or_b32 s36, s18, 21
	s_or_b32 s33, s18, 20
	s_waitcnt vmcnt(1)
	v_pk_fma_f32 v[2:3], v[98:99], v[44:45], v[2:3] op_sel_hi:[0,1,1]
	v_pk_fma_f32 v[6:7], v[98:99], v[46:47], v[6:7] op_sel_hi:[0,1,1]
	ds_read_b128 v[42:45], v62 offset:16416
	v_pk_fma_f32 v[10:11], v[98:99], v[30:31], v[10:11] op_sel_hi:[0,1,1]
	v_pk_fma_f32 v[14:15], v[98:99], v[48:49], v[14:15] op_sel_hi:[0,1,1]
	ds_read_b128 v[30:33], v62 offset:20512
	ds_read_b128 v[46:49], v62 offset:24608
	v_pk_fma_f32 v[54:55], v[100:101], v[4:5], v[2:3] op_sel_hi:[0,1,1]
	ds_read_b128 v[2:5], v62 offset:4144
	v_pk_fma_f32 v[56:57], v[100:101], v[8:9], v[6:7] op_sel_hi:[0,1,1]
	v_pk_fma_f32 v[84:85], v[100:101], v[12:13], v[10:11] op_sel_hi:[0,1,1]
	ds_read_b128 v[6:9], v62 offset:12336
	v_pk_fma_f32 v[86:87], v[100:101], v[16:17], v[14:15] op_sel_hi:[0,1,1]
	v_mov_b32_e32 v81, v18
	v_mov_b32_e32 v18, v39
	v_mov_b32_e32 v73, v20
	v_mov_b32_e32 v20, v41
	s_waitcnt lgkmcnt(4)
	v_mov_b32_e32 v82, v42
	v_mov_b32_e32 v83, v22
	v_mov_b32_e32 v22, v43
	v_mov_b32_e32 v74, v44
	v_mov_b32_e32 v75, v24
	v_mov_b32_e32 v24, v45
	ds_read_b128 v[42:45], v62 offset:24624
	s_waitcnt lgkmcnt(3)
	v_mov_b32_e32 v88, v46
	ds_read_b128 v[10:13], v62 offset:20528
	v_mov_b32_e32 v89, v30
	v_mov_b32_e32 v30, v47
	v_mov_b32_e32 v76, v48
	v_mov_b32_e32 v77, v32
	v_mov_b32_e32 v32, v49
	ds_read_b128 v[38:41], v62 offset:32800
	ds_read_b128 v[46:49], v62 offset:32816
	ds_read_b128 v[50:53], v62 offset:28704
	ds_read_b128 v[14:17], v62 offset:28720
	v_fmac_f32_e32 v93, v98, v78
	v_fmac_f32_e32 v93, v100, v79
	s_waitcnt lgkmcnt(3)
	v_mov_b32_e32 v90, v38
	s_waitcnt lgkmcnt(1)
	v_mov_b32_e32 v91, v50
	v_mov_b32_e32 v50, v39
	v_mov_b32_e32 v78, v40
	v_mov_b32_e32 v79, v52
	v_mov_b32_e32 v52, v41
	s_waitcnt vmcnt(0)
	v_pk_fma_f32 v[80:81], v[102:103], v[80:81], v[54:55] op_sel_hi:[0,1,1]
	v_pk_fma_f32 v[82:83], v[102:103], v[82:83], v[56:57] op_sel_hi:[0,1,1]
	ds_read_b128 v[54:57], v62 offset:32
	ds_read_b128 v[38:41], v62 offset:48
	v_pk_fma_f32 v[84:85], v[102:103], v[88:89], v[84:85] op_sel_hi:[0,1,1]
	v_pk_fma_f32 v[86:87], v[102:103], v[90:91], v[86:87] op_sel_hi:[0,1,1]
	v_mad_i64_i32 v[88:89], s[34:35], s19, v61, v[70:71]
	v_mad_i64_i32 v[90:91], s[34:35], s31, v61, v[70:71]
	v_mad_i64_i32 v[100:101], s[34:35], s38, v61, v[70:71]
	s_waitcnt lgkmcnt(1)
; template <int LO, int HI>
; DEV void run_phases(LAS unsigned char* lds, const int ph_lo, const int ph_hi, const int G, const int wave0, unsigned& nbar) {
;     ...
;                     for (int k = wave * 128; k < wave * 128 + 128; ++k) { const float wv = wm[(size_t)k * 6144];
; #pragma unroll
;                         for (int r = 0; r < 9; ++r) acc9[r] += sl[r * 1024 + k] * wv; }
	v_fmac_f32_e32 v93, v102, v54
	global_load_dword v54, v[88:89], off
	v_mad_i64_i32 v[98:99], s[34:35], s37, v61, v[70:71]
	global_load_dword v90, v[90:91], off
	v_mad_i64_i32 v[102:103], s[34:35], s39, v61, v[70:71]
	global_load_dword v96, v[96:97], off
	s_or_b32 s19, s18, 17
	global_load_dword v100, v[100:101], off
	v_mad_i64_i32 v[88:89], s[34:35], s21, v61, v[70:71]
	global_load_dword v88, v[88:89], off
	s_or_b32 s31, s18, 19
	global_load_dword v94, v[94:95], off
	s_or_b32 s38, s18, 23
	global_load_dword v98, v[98:99], off
	s_or_b32 s21, s18, 18
	global_load_dword v102, v[102:103], off
	s_or_b32 s37, s18, 22
	s_or_b32 s39, s18, 24
	s_waitcnt vmcnt(7)
	v_fmac_f32_e32 v93, v54, v55
	v_pk_fma_f32 v[18:19], v[54:55], v[18:19], v[80:81] op_sel_hi:[0,1,1]
	v_pk_fma_f32 v[22:23], v[54:55], v[22:23], v[82:83] op_sel_hi:[0,1,1]
	v_pk_fma_f32 v[30:31], v[54:55], v[30:31], v[84:85] op_sel_hi:[0,1,1]
	v_pk_fma_f32 v[50:51], v[54:55], v[50:51], v[86:87] op_sel_hi:[0,1,1]
	s_waitcnt vmcnt(3)
	v_fmac_f32_e32 v93, v88, v56
	v_pk_fma_f32 v[18:19], v[88:89], v[72:73], v[18:19] op_sel_hi:[0,1,1]
	v_pk_fma_f32 v[22:23], v[88:89], v[74:75], v[22:23] op_sel_hi:[0,1,1]
	v_pk_fma_f32 v[30:31], v[88:89], v[76:77], v[30:31] op_sel_hi:[0,1,1]
	v_fmac_f32_e32 v93, v90, v57
	v_pk_fma_f32 v[50:51], v[88:89], v[78:79], v[50:51] op_sel_hi:[0,1,1]
	v_pk_fma_f32 v[18:19], v[90:91], v[20:21], v[18:19] op_sel_hi:[0,1,1]
	v_pk_fma_f32 v[20:21], v[90:91], v[24:25], v[22:23] op_sel_hi:[0,1,1]
	v_pk_fma_f32 v[22:23], v[90:91], v[32:33], v[30:31] op_sel_hi:[0,1,1]
	v_mov_b32_e32 v30, v34
	v_mov_b32_e32 v31, v2
	s_waitcnt vmcnt(2) lgkmcnt(0)
	v_fmac_f32_e32 v93, v94, v38
	v_pk_fma_f32 v[24:25], v[90:91], v[52:53], v[50:51] op_sel_hi:[0,1,1]
	v_mov_b32_e32 v2, v35
	v_mov_b32_e32 v34, v26
	v_mov_b32_e32 v35, v6
	v_mov_b32_e32 v6, v27
	v_mov_b32_e32 v26, v28
	v_mov_b32_e32 v27, v8
	v_mov_b32_e32 v8, v29
	v_mov_b32_e32 v28, v42
	v_mov_b32_e32 v29, v10
	v_mov_b32_e32 v10, v43
	v_mov_b32_e32 v42, v46
	v_mov_b32_e32 v43, v14
	v_pk_fma_f32 v[30:31], v[94:95], v[30:31], v[18:19] op_sel_hi:[0,1,1]
	v_fmac_f32_e32 v93, v96, v39
	v_mov_b32_e32 v32, v36
	v_mov_b32_e32 v33, v4
	v_mov_b32_e32 v14, v47
	v_pk_fma_f32 v[22:23], v[94:95], v[28:29], v[22:23] op_sel_hi:[0,1,1]
	v_pk_fma_f32 v[24:25], v[94:95], v[42:43], v[24:25] op_sel_hi:[0,1,1]
	v_pk_fma_f32 v[2:3], v[96:97], v[2:3], v[30:31] op_sel_hi:[0,1,1]
	s_waitcnt vmcnt(1)
	v_fmac_f32_e32 v93, v98, v40
	v_mov_b32_e32 v4, v37
	v_mov_b32_e32 v36, v44
	v_mov_b32_e32 v37, v12
	v_mov_b32_e32 v12, v45
	v_mov_b32_e32 v50, v48
	v_mov_b32_e32 v51, v16
	v_mov_b32_e32 v16, v49
	v_pk_fma_f32 v[34:35], v[94:95], v[34:35], v[20:21] op_sel_hi:[0,1,1]
	ds_read_b128 v[18:21], v62 offset:4160
	ds_read_b128 v[42:45], v62 offset:8256
	v_pk_fma_f32 v[10:11], v[96:97], v[10:11], v[22:23] op_sel_hi:[0,1,1]
	v_pk_fma_f32 v[14:15], v[96:97], v[14:15], v[24:25] op_sel_hi:[0,1,1]
	ds_read_b128 v[22:25], v62 offset:12352
	v_pk_fma_f32 v[2:3], v[98:99], v[32:33], v[2:3] op_sel_hi:[0,1,1]
	ds_read_b128 v[46:49], v62 offset:16448
	ds_read_b128 v[30:33], v62 offset:20544
	v_fmac_f32_e32 v93, v100, v41
	ds_read_b128 v[38:41], v62 offset:24640
	v_pk_fma_f32 v[6:7], v[96:97], v[6:7], v[34:35] op_sel_hi:[0,1,1]
	v_pk_fma_f32 v[6:7], v[98:99], v[26:27], v[6:7] op_sel_hi:[0,1,1]
	v_pk_fma_f32 v[10:11], v[98:99], v[36:37], v[10:11] op_sel_hi:[0,1,1]
	v_pk_fma_f32 v[14:15], v[98:99], v[50:51], v[14:15] op_sel_hi:[0,1,1]
	v_pk_fma_f32 v[54:55], v[100:101], v[4:5], v[2:3] op_sel_hi:[0,1,1]
	ds_read_b128 v[2:5], v62 offset:4176
	v_pk_fma_f32 v[56:57], v[100:101], v[8:9], v[6:7] op_sel_hi:[0,1,1]
	ds_read_b128 v[34:37], v62 offset:8272
	v_pk_fma_f32 v[84:85], v[100:101], v[12:13], v[10:11] op_sel_hi:[0,1,1]
	ds_read_b128 v[6:9], v62 offset:12368
	v_pk_fma_f32 v[86:87], v[100:101], v[16:17], v[14:15] op_sel_hi:[0,1,1]
	ds_read_b128 v[26:29], v62 offset:16464
	s_waitcnt lgkmcnt(8)
	v_mov_b32_e32 v80, v42
	v_mov_b32_e32 v81, v18
	v_mov_b32_e32 v18, v43
	v_mov_b32_e32 v72, v44
	v_mov_b32_e32 v73, v20
	v_mov_b32_e32 v20, v45
	s_waitcnt lgkmcnt(6)
	v_mov_b32_e32 v82, v46
	v_mov_b32_e32 v83, v22
	v_mov_b32_e32 v22, v47
	v_mov_b32_e32 v74, v48
	v_mov_b32_e32 v75, v24
	v_mov_b32_e32 v24, v49
	ds_read_b128 v[42:45], v62 offset:24656
	s_waitcnt lgkmcnt(5)
	v_mov_b32_e32 v88, v38
	ds_read_b128 v[10:13], v62 offset:20560
	v_mov_b32_e32 v89, v30
	v_mov_b32_e32 v30, v39
	v_mov_b32_e32 v76, v40
	v_mov_b32_e32 v77, v32
	v_mov_b32_e32 v32, v41
	ds_read_b128 v[38:41], v62 offset:32832
	ds_read_b128 v[46:49], v62 offset:32848
	ds_read_b128 v[50:53], v62 offset:28736
	ds_read_b128 v[14:17], v62 offset:28752
	s_waitcnt vmcnt(0)
	v_pk_fma_f32 v[80:81], v[102:103], v[80:81], v[54:55] op_sel_hi:[0,1,1]
	v_pk_fma_f32 v[82:83], v[102:103], v[82:83], v[56:57] op_sel_hi:[0,1,1]
	s_waitcnt lgkmcnt(3)
	v_mov_b32_e32 v90, v38
	s_waitcnt lgkmcnt(1)
	v_mov_b32_e32 v91, v50
	v_mov_b32_e32 v50, v39
	v_mov_b32_e32 v78, v40
	v_mov_b32_e32 v79, v52
	v_mov_b32_e32 v52, v41
	ds_read_b128 v[54:57], v62 offset:64
	ds_read_b128 v[38:41], v62 offset:80
	v_pk_fma_f32 v[84:85], v[102:103], v[88:89], v[84:85] op_sel_hi:[0,1,1]
	v_pk_fma_f32 v[86:87], v[102:103], v[90:91], v[86:87] op_sel_hi:[0,1,1]
	v_mad_i64_i32 v[88:89], s[34:35], s19, v61, v[70:71]
	v_mad_i64_i32 v[90:91], s[34:35], s31, v61, v[70:71]
	v_mad_i64_i32 v[96:97], s[34:35], s36, v61, v[70:71]
	v_mad_i64_i32 v[100:101], s[34:35], s38, v61, v[70:71]
	s_waitcnt lgkmcnt(1)
; template <int LO, int HI>
; DEV void run_phases(LAS unsigned char* lds, const int ph_lo, const int ph_hi, const int G, const int wave0, unsigned& nbar) {
;     ...
;                     for (int k = wave * 128; k < wave * 128 + 128; ++k) { const float wv = wm[(size_t)k * 6144];
; #pragma unroll
;                         for (int r = 0; r < 9; ++r) acc9[r] += sl[r * 1024 + k] * wv; }
	v_fmac_f32_e32 v93, v102, v54
	global_load_dword v54, v[88:89], off
	v_mad_i64_i32 v[94:95], s[34:35], s33, v61, v[70:71]
	global_load_dword v90, v[90:91], off
	v_mad_i64_i32 v[98:99], s[34:35], s37, v61, v[70:71]
	global_load_dword v96, v[96:97], off
	v_mad_i64_i32 v[102:103], s[34:35], s39, v61, v[70:71]
	global_load_dword v100, v[100:101], off
	v_mad_i64_i32 v[88:89], s[34:35], s21, v61, v[70:71]
	global_load_dword v88, v[88:89], off
	s_or_b32 s19, s18, 25
	global_load_dword v94, v[94:95], off
	s_or_b32 s37, s18, 30
	global_load_dword v98, v[98:99], off
	s_or_b32 s21, s18, 26
	global_load_dword v102, v[102:103], off
	s_or_b32 s38, s18, 31
	s_or_b32 s31, s18, 27
	s_or_b32 s33, s18, 28
	s_or_b32 s36, s18, 29
	s_waitcnt vmcnt(7)
	v_pk_fma_f32 v[18:19], v[54:55], v[18:19], v[80:81] op_sel_hi:[0,1,1]
	v_pk_fma_f32 v[22:23], v[54:55], v[22:23], v[82:83] op_sel_hi:[0,1,1]
	v_pk_fma_f32 v[30:31], v[54:55], v[30:31], v[84:85] op_sel_hi:[0,1,1]
	v_pk_fma_f32 v[50:51], v[54:55], v[50:51], v[86:87] op_sel_hi:[0,1,1]
	v_fmac_f32_e32 v93, v54, v55
	s_waitcnt vmcnt(3)
	v_pk_fma_f32 v[18:19], v[88:89], v[72:73], v[18:19] op_sel_hi:[0,1,1]
	v_pk_fma_f32 v[22:23], v[88:89], v[74:75], v[22:23] op_sel_hi:[0,1,1]
	v_pk_fma_f32 v[30:31], v[88:89], v[76:77], v[30:31] op_sel_hi:[0,1,1]
	v_pk_fma_f32 v[50:51], v[88:89], v[78:79], v[50:51] op_sel_hi:[0,1,1]
	v_pk_fma_f32 v[18:19], v[90:91], v[20:21], v[18:19] op_sel_hi:[0,1,1]
	v_pk_fma_f32 v[20:21], v[90:91], v[24:25], v[22:23] op_sel_hi:[0,1,1]
	v_pk_fma_f32 v[22:23], v[90:91], v[32:33], v[30:31] op_sel_hi:[0,1,1]
	v_pk_fma_f32 v[24:25], v[90:91], v[52:53], v[50:51] op_sel_hi:[0,1,1]
	v_mov_b32_e32 v30, v34
	v_mov_b32_e32 v31, v2
	v_mov_b32_e32 v2, v35
	v_mov_b32_e32 v34, v26
	v_mov_b32_e32 v35, v6
	v_mov_b32_e32 v6, v27
	v_mov_b32_e32 v26, v28
	v_mov_b32_e32 v27, v8
	v_mov_b32_e32 v8, v29
	v_mov_b32_e32 v28, v42
	v_mov_b32_e32 v29, v10
	v_mov_b32_e32 v50, v46
	v_mov_b32_e32 v51, v14
	v_mov_b32_e32 v10, v43
	v_mov_b32_e32 v14, v47
	s_waitcnt vmcnt(2)
	v_pk_fma_f32 v[30:31], v[94:95], v[30:31], v[18:19] op_sel_hi:[0,1,1]
	v_pk_fma_f32 v[22:23], v[94:95], v[28:29], v[22:23] op_sel_hi:[0,1,1]
	v_pk_fma_f32 v[24:25], v[94:95], v[50:51], v[24:25] op_sel_hi:[0,1,1]
	v_mov_b32_e32 v32, v36
	v_mov_b32_e32 v33, v4
	v_mov_b32_e32 v4, v37
	v_mov_b32_e32 v36, v44
	v_mov_b32_e32 v37, v12
	v_mov_b32_e32 v52, v48
	v_mov_b32_e32 v53, v16
	v_pk_fma_f32 v[34:35], v[94:95], v[34:35], v[20:21] op_sel_hi:[0,1,1]
	v_pk_fma_f32 v[2:3], v[96:97], v[2:3], v[30:31] op_sel_hi:[0,1,1]
	v_pk_fma_f32 v[10:11], v[96:97], v[10:11], v[22:23] op_sel_hi:[0,1,1]
	v_pk_fma_f32 v[14:15], v[96:97], v[14:15], v[24:25] op_sel_hi:[0,1,1]
	v_fmac_f32_e32 v93, v88, v56
	v_mov_b32_e32 v12, v45
	v_mov_b32_e32 v16, v49
	ds_read_b128 v[42:45], v62 offset:4192
	ds_read_b128 v[18:21], v62 offset:8288
	v_pk_fma_f32 v[6:7], v[96:97], v[6:7], v[34:35] op_sel_hi:[0,1,1]
	ds_read_b128 v[46:49], v62 offset:12384
	s_waitcnt vmcnt(1)
	v_pk_fma_f32 v[2:3], v[98:99], v[32:33], v[2:3] op_sel_hi:[0,1,1]
	ds_read_b128 v[30:33], v62 offset:16480
	ds_read_b128 v[22:25], v62 offset:16496
	v_pk_fma_f32 v[10:11], v[98:99], v[36:37], v[10:11] op_sel_hi:[0,1,1]
	v_pk_fma_f32 v[14:15], v[98:99], v[52:53], v[14:15] op_sel_hi:[0,1,1]
	ds_read_b128 v[50:53], v62 offset:20576
	ds_read_b128 v[34:37], v62 offset:24672
	v_fmac_f32_e32 v93, v90, v57
	s_waitcnt lgkmcnt(7)
	v_fmac_f32_e32 v93, v94, v38
	v_fmac_f32_e32 v93, v96, v39
	v_pk_fma_f32 v[6:7], v[98:99], v[26:27], v[6:7] op_sel_hi:[0,1,1]
	v_fmac_f32_e32 v93, v98, v40
	v_fmac_f32_e32 v93, v100, v41
	v_pk_fma_f32 v[54:55], v[100:101], v[4:5], v[2:3] op_sel_hi:[0,1,1]
	ds_read_b128 v[2:5], v62 offset:4208
	v_pk_fma_f32 v[56:57], v[100:101], v[8:9], v[6:7] op_sel_hi:[0,1,1]
	ds_read_b128 v[26:29], v62 offset:8304
	v_pk_fma_f32 v[72:73], v[100:101], v[12:13], v[10:11] op_sel_hi:[0,1,1]
	ds_read_b128 v[6:9], v62 offset:12400
	v_pk_fma_f32 v[74:75], v[100:101], v[16:17], v[14:15] op_sel_hi:[0,1,1]
	s_waitcnt lgkmcnt(8)
	v_mov_b32_e32 v84, v18
	v_mov_b32_e32 v85, v42
	v_mov_b32_e32 v42, v19
	v_mov_b32_e32 v76, v20
	v_mov_b32_e32 v77, v44
	v_mov_b32_e32 v44, v21
	s_waitcnt lgkmcnt(6)
	v_mov_b32_e32 v86, v30
	v_mov_b32_e32 v87, v46
	v_mov_b32_e32 v46, v31
	v_mov_b32_e32 v78, v32
	v_mov_b32_e32 v79, v48
	v_mov_b32_e32 v48, v33
	ds_read_b128 v[30:33], v62 offset:24688
	s_waitcnt lgkmcnt(4)
	v_mov_b32_e32 v88, v34
	ds_read_b128 v[10:13], v62 offset:20592
	v_mov_b32_e32 v89, v50
	v_mov_b32_e32 v50, v35
	v_mov_b32_e32 v80, v36
	v_mov_b32_e32 v81, v52
	v_mov_b32_e32 v52, v37
	ds_read_b128 v[18:21], v62 offset:32864
	ds_read_b128 v[34:37], v62 offset:32880
	ds_read_b128 v[38:41], v62 offset:28768
	ds_read_b128 v[14:17], v62 offset:28784
	s_waitcnt vmcnt(0)
	v_pk_fma_f32 v[84:85], v[102:103], v[84:85], v[54:55] op_sel_hi:[0,1,1]
	v_pk_fma_f32 v[86:87], v[102:103], v[86:87], v[56:57] op_sel_hi:[0,1,1]
	s_waitcnt lgkmcnt(3)
; #define KIN(i) (((const float* const __attribute__((address_space(4)))*)kp)[i])
; template <int LO, int HI>
; DEV void run_phases(LAS unsigned char* lds, const int ph_lo, const int ph_hi, const int G, const int wave0, unsigned& nbar) {
;     ...
;                     for (int k = wave * 128; k < wave * 128 + 128; ++k) { const float wv = wm[(size_t)k * 6144];
; #pragma unroll
;                         for (int r = 0; r < 9; ++r) acc9[r] += sl[r * 1024 + k] * wv; }
; #pragma unroll
;                     for (int r = 0; r < 9; ++r) part[(wave * 9 + r) * 64 + lane] = acc9[r];
;                     __syncthreads();
;                     for (int i = tid; i < 576; i += NTHREADS) { const int r = i >> 6, ln = i & 63; float s = 0.f;
; #pragma unroll
;                         for (int w = 0; w < 8; ++w) s += part[(w * 9 + r) * 64 + ln];
;                         mod[(size_t)(l * 9 + r) * 6144 + n0 + ln] = s + KIN(I_BMOD)[l * 6144 + n0 + ln]; }
	v_mov_b32_e32 v90, v18
	s_waitcnt lgkmcnt(1)
	v_mov_b32_e32 v91, v38
	v_mov_b32_e32 v38, v19
	v_mov_b32_e32 v82, v20
	v_mov_b32_e32 v83, v40
	v_mov_b32_e32 v40, v21
	ds_read_b128 v[54:57], v62 offset:96
	ds_read_b128 v[18:21], v62 offset:112
	v_pk_fma_f32 v[88:89], v[102:103], v[88:89], v[72:73] op_sel_hi:[0,1,1]
	v_mad_i64_i32 v[72:73], s[34:35], s19, v61, v[70:71]
	v_mad_i64_i32 v[100:101], s[34:35], s37, v61, v[70:71]
	global_load_dword v94, v[72:73], off
	global_load_dword v62, v[100:101], off
	v_mad_i64_i32 v[72:73], s[34:35], s21, v61, v[70:71]
	v_mad_i64_i32 v[100:101], s[34:35], s38, v61, v[70:71]
	s_waitcnt lgkmcnt(1)
	v_fmac_f32_e32 v93, v102, v54
	global_load_dword v96, v[72:73], off
	global_load_dword v54, v[100:101], off
	v_mad_i64_i32 v[72:73], s[34:35], s31, v61, v[70:71]
	global_load_dword v98, v[72:73], off
	v_mad_i64_i32 v[72:73], s[34:35], s33, v61, v[70:71]
	v_pk_fma_f32 v[90:91], v[102:103], v[90:91], v[74:75] op_sel_hi:[0,1,1]
	global_load_dword v74, v[72:73], off
	v_mad_i64_i32 v[72:73], s[34:35], s36, v61, v[70:71]
	global_load_dword v72, v[72:73], off
	s_add_i32 s19, s18, 32
	s_cmp_lg_u32 s18, s25
	s_mov_b32 s18, s19
	s_waitcnt vmcnt(6)
	v_fmac_f32_e32 v93, v94, v55
	v_pk_fma_f32 v[42:43], v[94:95], v[42:43], v[84:85] op_sel_hi:[0,1,1]
	v_pk_fma_f32 v[46:47], v[94:95], v[46:47], v[86:87] op_sel_hi:[0,1,1]
	v_pk_fma_f32 v[50:51], v[94:95], v[50:51], v[88:89] op_sel_hi:[0,1,1]
	v_pk_fma_f32 v[38:39], v[94:95], v[38:39], v[90:91] op_sel_hi:[0,1,1]
	s_waitcnt vmcnt(4)
	v_pk_fma_f32 v[42:43], v[96:97], v[76:77], v[42:43] op_sel_hi:[0,1,1]
	v_pk_fma_f32 v[46:47], v[96:97], v[78:79], v[46:47] op_sel_hi:[0,1,1]
	v_pk_fma_f32 v[50:51], v[96:97], v[80:81], v[50:51] op_sel_hi:[0,1,1]
	v_pk_fma_f32 v[76:77], v[96:97], v[82:83], v[38:39] op_sel_hi:[0,1,1]
	v_fmac_f32_e32 v93, v96, v56
	s_waitcnt vmcnt(2)
	v_fmac_f32_e32 v93, v98, v57
	v_pk_fma_f32 v[38:39], v[98:99], v[44:45], v[42:43] op_sel_hi:[0,1,1]
	v_pk_fma_f32 v[42:43], v[98:99], v[48:49], v[46:47] op_sel_hi:[0,1,1]
	v_pk_fma_f32 v[44:45], v[98:99], v[52:53], v[50:51] op_sel_hi:[0,1,1]
	v_pk_fma_f32 v[40:41], v[98:99], v[40:41], v[76:77] op_sel_hi:[0,1,1]
	v_mov_b32_e32 v46, v26
	v_mov_b32_e32 v47, v2
	v_mov_b32_e32 v2, v27
	v_mov_b32_e32 v26, v28
	v_mov_b32_e32 v27, v4
	v_mov_b32_e32 v4, v29
	v_mov_b32_e32 v28, v22
	v_mov_b32_e32 v29, v6
	v_mov_b32_e32 v6, v23
	v_mov_b32_e32 v22, v24
	v_mov_b32_e32 v23, v8
	v_mov_b32_e32 v8, v25
	v_mov_b32_e32 v24, v30
	v_mov_b32_e32 v25, v10
	v_mov_b32_e32 v10, v31
	v_mov_b32_e32 v30, v32
	v_mov_b32_e32 v31, v12
	v_mov_b32_e32 v12, v33
	v_mov_b32_e32 v32, v34
	v_mov_b32_e32 v33, v14
	v_mov_b32_e32 v14, v35
	v_mov_b32_e32 v34, v36
	v_mov_b32_e32 v35, v16
	v_mov_b32_e32 v16, v37
	s_waitcnt vmcnt(1) lgkmcnt(0)
	v_fmac_f32_e32 v93, v74, v18
	v_pk_fma_f32 v[36:37], v[74:75], v[46:47], v[38:39] op_sel_hi:[0,1,1]
	v_pk_fma_f32 v[28:29], v[74:75], v[28:29], v[42:43] op_sel_hi:[0,1,1]
	v_pk_fma_f32 v[24:25], v[74:75], v[24:25], v[44:45] op_sel_hi:[0,1,1]
	v_pk_fma_f32 v[32:33], v[74:75], v[32:33], v[40:41] op_sel_hi:[0,1,1]
	s_waitcnt vmcnt(0)
	v_fmac_f32_e32 v93, v72, v19
	v_pk_fma_f32 v[2:3], v[72:73], v[2:3], v[36:37] op_sel_hi:[0,1,1]
	v_pk_fma_f32 v[6:7], v[72:73], v[6:7], v[28:29] op_sel_hi:[0,1,1]
	v_pk_fma_f32 v[10:11], v[72:73], v[10:11], v[24:25] op_sel_hi:[0,1,1]
	v_pk_fma_f32 v[14:15], v[72:73], v[14:15], v[32:33] op_sel_hi:[0,1,1]
	v_fmac_f32_e32 v93, v62, v20
	v_pk_fma_f32 v[2:3], v[62:63], v[26:27], v[2:3] op_sel_hi:[0,1,1]
	v_pk_fma_f32 v[6:7], v[62:63], v[22:23], v[6:7] op_sel_hi:[0,1,1]
	v_pk_fma_f32 v[10:11], v[62:63], v[30:31], v[10:11] op_sel_hi:[0,1,1]
	v_pk_fma_f32 v[14:15], v[62:63], v[34:35], v[14:15] op_sel_hi:[0,1,1]
	v_fmac_f32_e32 v93, v54, v21
	v_pk_fma_f32 v[78:79], v[54:55], v[4:5], v[2:3] op_sel_hi:[0,1,1]
	v_pk_fma_f32 v[76:77], v[54:55], v[8:9], v[6:7] op_sel_hi:[0,1,1]
	v_pk_fma_f32 v[74:75], v[54:55], v[12:13], v[10:11] op_sel_hi:[0,1,1]
	v_pk_fma_f32 v[72:73], v[54:55], v[16:17], v[14:15] op_sel_hi:[0,1,1]
	s_cbranch_scc1 .LBB0_14
	v_add_u32_e32 v2, s24, v92
	ds_write2st64_b32 v2, v93, v79 offset0:144 offset1:145
	ds_write2st64_b32 v2, v78, v77 offset0:146 offset1:147
	ds_write2st64_b32 v2, v76, v75 offset0:148 offset1:149
	ds_write2st64_b32 v2, v74, v73 offset0:150 offset1:151
	ds_write_b32 v2, v72 offset:38912
	s_waitcnt lgkmcnt(0)
	s_barrier
	s_and_saveexec_b64 s[18:19], s[4:5]
	s_cbranch_execz .LBB0_3
	s_load_dwordx2 s[34:35], s[14:15], 0x38
	s_mul_i32 s21, s20, 0x1800
	s_add_i32 s21, s21, s12
	v_or_b32_e32 v2, s21, v58
	v_ashrrev_i32_e32 v3, 31, v2
	s_mul_i32 s20, s20, 9
	s_waitcnt lgkmcnt(0)
	v_lshl_add_u64 v[2:3], v[2:3], 2, s[34:35]
	v_lshl_add_u64 v[4:5], s[12:13], 2, v[64:65]
	s_mov_b64 s[12:13], 0
	v_mov_b32_e32 v6, v60
